# proj_a and proj_b GEMM epilogues: gate / accumulate loads issued one to six row-tiles ahead into spare registers, counted waits so result stores stay in flight
# speedup vs baseline: 1.4732x; 1.0028x over previous
; __device__ __forceinline__ unsigned pk2(float lo, float hi) { return f2bf(lo) | (f2bf(hi) << 16); }
;     __device__ __forceinline__ void operator()(const f32x4 (&acc)[2][2][4][2], const pg8::Unit& u, int wr, int wc, int fr, int fq) const {
;     ...
;                     } else if constexpr (MODE == 2 || MODE == 3) {
;                         const u32x4 g = *(const u32x4*)(aux + row * 4096 + (MODE == 3 ? 2048 : 0) + col);
;                         float r[8] = {v0[0], v0[1], v0[2], v0[3], v1[0], v1[1], v1[2], v1[3]};
;                         const unsigned gw[4] = {g.x, g.y, g.z, g.w};
; #pragma unroll
;                         for (int i = 0; i < 4; ++i) { r[2 * i] *= bf2f(gw[i] & 0xffffu); r[2 * i + 1] *= __builtin_bit_cast(float, gw[i] & 0xffff0000u); }
;                         if constexpr (MODE == 3) { const u32x4 pv = *(const u32x4*)(ob + row * 2048 + col); const unsigned pw[4] = {pv.x, pv.y, pv.z, pv.w};
; #pragma unroll
;                             for (int i = 0; i < 4; ++i) { r[2 * i] += bf2f(pw[i] & 0xffffu); r[2 * i + 1] += __builtin_bit_cast(float, pw[i] & 0xffff0000u); } }
;                         u32x4 w; w.x = pk2(r[0], r[1]); w.y = pk2(r[2], r[3]); w.z = pk2(r[4], r[5]); w.w = pk2(r[6], r[7]);
;                         *(u32x4*)(ob + row * 2048 + col) = w;
.LBB0_100:
	v_lshl_add_u32 v140, s9, 8, v142
	v_lshl_or_b32 v138, s8, 8, v144
	v_ashrrev_i32_e32 v141, 31, v140
	v_lshlrev_b64 v[146:147], 13, v[140:141]
	v_ashrrev_i32_e32 v139, 31, v138
	v_lshl_add_u64 v[146:147], s[24:25], 0, v[146:147]
	v_lshlrev_b64 v[138:139], 1, v[138:139]
	v_lshl_add_u64 v[152:153], v[146:147], 0, v[138:139]
	global_load_dwordx4 v[184:187], v[152:153], off
	global_load_dwordx4 v[188:191], v[152:153], off offset:256
	v_or_b32_e32 v242, 16, v140
	v_ashrrev_i32_e32 v243, 31, v242
	v_lshlrev_b64 v[244:245], 13, v[242:243]
	v_lshl_add_u64 v[242:243], s[24:25], 0, v[244:245]
	v_lshl_add_u64 v[242:243], v[242:243], 0, v[138:139]
	global_load_dwordx4 v[192:195], v[242:243], off
	global_load_dwordx4 v[196:199], v[242:243], off offset:256
	v_or_b32_e32 v242, 32, v140
	v_ashrrev_i32_e32 v243, 31, v242
	v_lshlrev_b64 v[244:245], 13, v[242:243]
	v_lshl_add_u64 v[242:243], s[24:25], 0, v[244:245]
	v_lshl_add_u64 v[242:243], v[242:243], 0, v[138:139]
	global_load_dwordx4 v[200:203], v[242:243], off
	global_load_dwordx4 v[214:217], v[242:243], off offset:256
	v_or_b32_e32 v242, 48, v140
	v_ashrrev_i32_e32 v243, 31, v242
	v_lshlrev_b64 v[244:245], 13, v[242:243]
	v_lshl_add_u64 v[242:243], s[24:25], 0, v[244:245]
	v_lshl_add_u64 v[242:243], v[242:243], 0, v[138:139]
	global_load_dwordx4 v[218:221], v[242:243], off
	global_load_dwordx4 v[222:225], v[242:243], off offset:256
	v_add_u32_e32 v242, 0x80, v140
	v_ashrrev_i32_e32 v243, 31, v242
	v_lshlrev_b64 v[244:245], 13, v[242:243]
	v_lshl_add_u64 v[242:243], s[24:25], 0, v[244:245]
	v_lshl_add_u64 v[242:243], v[242:243], 0, v[138:139]
	global_load_dwordx4 v[226:229], v[242:243], off
	global_load_dwordx4 v[230:233], v[242:243], off offset:256
	v_add_u32_e32 v242, 0x90, v140
	v_ashrrev_i32_e32 v243, 31, v242
	v_lshlrev_b64 v[244:245], 13, v[242:243]
	v_lshl_add_u64 v[242:243], s[24:25], 0, v[244:245]
	v_lshl_add_u64 v[242:243], v[242:243], 0, v[138:139]
	global_load_dwordx4 v[234:237], v[242:243], off
	global_load_dwordx4 v[238:241], v[242:243], off offset:256
	v_mov_b32_e32 v157, v126
	v_mov_b32_e32 v126, v125
	v_mov_b32_e32 v156, v124
	v_lshlrev_b64 v[150:151], 12, v[140:141]
	s_mov_b64 s[42:43], -1
	s_andn2_b64 vcc, exec, s[38:39]
	s_waitcnt vmcnt(10)
	v_lshlrev_b32_e32 v155, 16, v185
	v_lshlrev_b32_e32 v154, 16, v184
	v_and_b32_e32 v147, 0xffff0000, v185
	v_and_b32_e32 v146, 0xffff0000, v184
	v_pk_mul_f32 v[124:125], v[126:127], v[146:147]
	v_lshlrev_b32_e32 v127, 16, v187
	v_lshlrev_b32_e32 v126, 16, v186
	v_mov_b32_e32 v146, v120
	v_mov_b32_e32 v147, v122
	v_pk_mul_f32 v[126:127], v[146:147], v[126:127]
	v_and_b32_e32 v147, 0xffff0000, v187
	v_and_b32_e32 v146, 0xffff0000, v186
	v_mov_b32_e32 v122, v121
	v_pk_mul_f32 v[120:121], v[122:123], v[146:147]
	v_pk_mul_f32 v[154:155], v[156:157], v[154:155]
	v_cvt_pk_bf16_f32 v123, v155, v125
	v_cvt_pk_bf16_f32 v122, v154, v124
	v_cvt_pk_bf16_f32 v125, v127, v121
	v_cvt_pk_bf16_f32 v124, v126, v120
	v_lshl_add_u64 v[120:121], s[26:27], 0, v[150:151]
	v_lshl_add_u64 v[120:121], v[120:121], 0, v[138:139]
	global_store_dwordx4 v[120:121], v[122:125], off
	v_mov_b32_e32 v147, v118
	v_mov_b32_e32 v118, v117
	v_mov_b32_e32 v146, v116
	v_lshlrev_b32_e32 v123, 16, v189
	v_lshlrev_b32_e32 v122, 16, v188
	v_and_b32_e32 v125, 0xffff0000, v189
	v_and_b32_e32 v124, 0xffff0000, v188
	v_pk_mul_f32 v[116:117], v[118:119], v[124:125]
	v_lshlrev_b32_e32 v119, 16, v191
	v_lshlrev_b32_e32 v118, 16, v190
	v_mov_b32_e32 v124, v112
	v_mov_b32_e32 v125, v114
	v_pk_mul_f32 v[118:119], v[124:125], v[118:119]
	v_and_b32_e32 v125, 0xffff0000, v191
	v_and_b32_e32 v124, 0xffff0000, v190
	v_mov_b32_e32 v114, v113
	v_pk_mul_f32 v[112:113], v[114:115], v[124:125]
	v_pk_mul_f32 v[122:123], v[146:147], v[122:123]
	v_cvt_pk_bf16_f32 v115, v119, v113
	v_cvt_pk_bf16_f32 v114, v118, v112
	v_cvt_pk_bf16_f32 v113, v123, v117
	v_cvt_pk_bf16_f32 v112, v122, v116
	global_store_dwordx4 v[120:121], v[112:115], off offset:256
	v_mov_b32_e32 v123, v110
	v_mov_b32_e32 v110, v109
	v_or_b32_e32 v112, 16, v140
	v_ashrrev_i32_e32 v113, 31, v112
	v_lshlrev_b64 v[114:115], 13, v[112:113]
	v_lshlrev_b64 v[118:119], 12, v[112:113]
	v_lshl_add_u64 v[112:113], s[24:25], 0, v[114:115]
	v_lshl_add_u64 v[112:113], v[112:113], 0, v[138:139]
	v_add_u32_e32 v242, 0xa0, v140
	v_ashrrev_i32_e32 v243, 31, v242
	v_lshlrev_b64 v[244:245], 13, v[242:243]
	v_lshl_add_u64 v[242:243], s[24:25], 0, v[244:245]
	v_lshl_add_u64 v[242:243], v[242:243], 0, v[138:139]
	global_load_dwordx4 v[184:187], v[242:243], off
	global_load_dwordx4 v[188:191], v[242:243], off offset:256
	v_mov_b32_e32 v122, v108
	s_waitcnt vmcnt(12)
; __device__ __forceinline__ unsigned pk2(float lo, float hi) { return f2bf(lo) | (f2bf(hi) << 16); }
;     __device__ __forceinline__ void operator()(const f32x4 (&acc)[2][2][4][2], const pg8::Unit& u, int wr, int wc, int fr, int fq) const {
;     ...
;                     } else if constexpr (MODE == 2 || MODE == 3) {
;                         const u32x4 g = *(const u32x4*)(aux + row * 4096 + (MODE == 3 ? 2048 : 0) + col);
;                         float r[8] = {v0[0], v0[1], v0[2], v0[3], v1[0], v1[1], v1[2], v1[3]};
;                         const unsigned gw[4] = {g.x, g.y, g.z, g.w};
; #pragma unroll
;                         for (int i = 0; i < 4; ++i) { r[2 * i] *= bf2f(gw[i] & 0xffffu); r[2 * i + 1] *= __builtin_bit_cast(float, gw[i] & 0xffff0000u); }
;                         if constexpr (MODE == 3) { const u32x4 pv = *(const u32x4*)(ob + row * 2048 + col); const unsigned pw[4] = {pv.x, pv.y, pv.z, pv.w};
; #pragma unroll
;                             for (int i = 0; i < 4; ++i) { r[2 * i] += bf2f(pw[i] & 0xffffu); r[2 * i + 1] += __builtin_bit_cast(float, pw[i] & 0xffff0000u); } }
;                         u32x4 w; w.x = pk2(r[0], r[1]); w.y = pk2(r[2], r[3]); w.z = pk2(r[4], r[5]); w.w = pk2(r[6], r[7]);
;                         *(u32x4*)(ob + row * 2048 + col) = w;
	v_lshlrev_b32_e32 v121, 16, v193
	v_lshlrev_b32_e32 v120, 16, v192
	v_and_b32_e32 v115, 0xffff0000, v193
	v_and_b32_e32 v114, 0xffff0000, v192
	v_pk_mul_f32 v[108:109], v[110:111], v[114:115]
	v_lshlrev_b32_e32 v111, 16, v195
	v_lshlrev_b32_e32 v110, 16, v194
	v_mov_b32_e32 v114, v104
	v_mov_b32_e32 v115, v106
	v_pk_mul_f32 v[110:111], v[114:115], v[110:111]
	v_and_b32_e32 v115, 0xffff0000, v195
	v_and_b32_e32 v114, 0xffff0000, v194
	v_mov_b32_e32 v106, v105
	v_pk_mul_f32 v[104:105], v[106:107], v[114:115]
	v_pk_mul_f32 v[120:121], v[122:123], v[120:121]
	v_cvt_pk_bf16_f32 v107, v121, v109
	v_cvt_pk_bf16_f32 v106, v120, v108
	v_cvt_pk_bf16_f32 v109, v111, v105
	v_cvt_pk_bf16_f32 v108, v110, v104
	v_lshl_add_u64 v[104:105], s[26:27], 0, v[118:119]
	v_lshl_add_u64 v[104:105], v[104:105], 0, v[138:139]
	global_store_dwordx4 v[104:105], v[106:109], off
	v_mov_b32_e32 v113, v102
	v_mov_b32_e32 v102, v101
	v_mov_b32_e32 v112, v100
	v_lshlrev_b32_e32 v107, 16, v197
	v_lshlrev_b32_e32 v106, 16, v196
	v_and_b32_e32 v109, 0xffff0000, v197
	v_and_b32_e32 v108, 0xffff0000, v196
	v_pk_mul_f32 v[102:103], v[102:103], v[108:109]
	v_lshlrev_b32_e32 v101, 16, v199
	v_lshlrev_b32_e32 v100, 16, v198
	v_mov_b32_e32 v108, v96
	v_mov_b32_e32 v109, v98
	v_pk_mul_f32 v[100:101], v[108:109], v[100:101]
	v_and_b32_e32 v109, 0xffff0000, v199
	v_and_b32_e32 v108, 0xffff0000, v198
	v_mov_b32_e32 v98, v97
	v_pk_mul_f32 v[96:97], v[98:99], v[108:109]
	v_pk_mul_f32 v[106:107], v[112:113], v[106:107]
	v_cvt_pk_bf16_f32 v99, v101, v97
	v_cvt_pk_bf16_f32 v98, v100, v96
	v_cvt_pk_bf16_f32 v97, v107, v103
	v_cvt_pk_bf16_f32 v96, v106, v102
	global_store_dwordx4 v[104:105], v[96:99], off offset:256
	v_mov_b32_e32 v107, v94
	v_mov_b32_e32 v94, v93
	v_or_b32_e32 v96, 32, v140
	v_ashrrev_i32_e32 v97, 31, v96
	v_lshlrev_b64 v[98:99], 13, v[96:97]
	v_lshlrev_b64 v[102:103], 12, v[96:97]
	v_lshl_add_u64 v[96:97], s[24:25], 0, v[98:99]
	v_lshl_add_u64 v[96:97], v[96:97], 0, v[138:139]
	v_add_u32_e32 v242, 0xb0, v140
	v_ashrrev_i32_e32 v243, 31, v242
	v_lshlrev_b64 v[244:245], 13, v[242:243]
	v_lshl_add_u64 v[242:243], s[24:25], 0, v[244:245]
	v_lshl_add_u64 v[242:243], v[242:243], 0, v[138:139]
	global_load_dwordx4 v[192:195], v[242:243], off
	global_load_dwordx4 v[196:199], v[242:243], off offset:256
	v_mov_b32_e32 v106, v92
	s_waitcnt vmcnt(14)
	v_lshlrev_b32_e32 v105, 16, v201
	v_lshlrev_b32_e32 v104, 16, v200
	v_and_b32_e32 v99, 0xffff0000, v201
	v_and_b32_e32 v98, 0xffff0000, v200
	v_pk_mul_f32 v[92:93], v[94:95], v[98:99]
	v_lshlrev_b32_e32 v95, 16, v203
	v_lshlrev_b32_e32 v94, 16, v202
	v_mov_b32_e32 v98, v88
	v_mov_b32_e32 v99, v90
	v_pk_mul_f32 v[94:95], v[98:99], v[94:95]
	v_and_b32_e32 v99, 0xffff0000, v203
	v_and_b32_e32 v98, 0xffff0000, v202
	v_mov_b32_e32 v90, v89
	v_pk_mul_f32 v[88:89], v[90:91], v[98:99]
	v_pk_mul_f32 v[104:105], v[106:107], v[104:105]
	v_cvt_pk_bf16_f32 v91, v105, v93
	v_cvt_pk_bf16_f32 v90, v104, v92
	v_cvt_pk_bf16_f32 v93, v95, v89
	v_cvt_pk_bf16_f32 v92, v94, v88
	v_lshl_add_u64 v[88:89], s[26:27], 0, v[102:103]
	v_lshl_add_u64 v[88:89], v[88:89], 0, v[138:139]
	global_store_dwordx4 v[88:89], v[90:93], off
	v_mov_b32_e32 v97, v86
	v_mov_b32_e32 v86, v85
	v_mov_b32_e32 v96, v84
	v_lshlrev_b32_e32 v91, 16, v215
	v_lshlrev_b32_e32 v90, 16, v214
	v_and_b32_e32 v93, 0xffff0000, v215
	v_and_b32_e32 v92, 0xffff0000, v214
	v_pk_mul_f32 v[84:85], v[86:87], v[92:93]
	v_lshlrev_b32_e32 v87, 16, v217
	v_lshlrev_b32_e32 v86, 16, v216
	v_mov_b32_e32 v92, v80
	v_mov_b32_e32 v93, v82
	v_pk_mul_f32 v[86:87], v[92:93], v[86:87]
	v_and_b32_e32 v93, 0xffff0000, v217
	v_and_b32_e32 v92, 0xffff0000, v216
	v_mov_b32_e32 v82, v81
	v_pk_mul_f32 v[80:81], v[82:83], v[92:93]
	v_pk_mul_f32 v[90:91], v[96:97], v[90:91]
	v_cvt_pk_bf16_f32 v83, v87, v81
	v_cvt_pk_bf16_f32 v82, v86, v80
	v_cvt_pk_bf16_f32 v81, v91, v85
	v_cvt_pk_bf16_f32 v80, v90, v84
	global_store_dwordx4 v[88:89], v[80:83], off offset:256
	v_mov_b32_e32 v91, v78
	v_mov_b32_e32 v78, v77
	v_or_b32_e32 v80, 48, v140
	v_ashrrev_i32_e32 v81, 31, v80
	v_lshlrev_b64 v[82:83], 13, v[80:81]
	v_lshlrev_b64 v[86:87], 12, v[80:81]
	v_lshl_add_u64 v[80:81], s[24:25], 0, v[82:83]
	v_lshl_add_u64 v[80:81], v[80:81], 0, v[138:139]
	v_mov_b32_e32 v90, v76
	s_waitcnt vmcnt(14)
	v_lshlrev_b32_e32 v89, 16, v219
	v_lshlrev_b32_e32 v88, 16, v218
	v_and_b32_e32 v83, 0xffff0000, v219
	v_and_b32_e32 v82, 0xffff0000, v218
	v_pk_mul_f32 v[76:77], v[78:79], v[82:83]
	v_lshlrev_b32_e32 v79, 16, v221
	v_lshlrev_b32_e32 v78, 16, v220
	v_mov_b32_e32 v82, v72
	v_mov_b32_e32 v83, v74
	v_pk_mul_f32 v[78:79], v[82:83], v[78:79]
	v_and_b32_e32 v83, 0xffff0000, v221
	v_and_b32_e32 v82, 0xffff0000, v220
	v_mov_b32_e32 v74, v73
	v_pk_mul_f32 v[72:73], v[74:75], v[82:83]
	v_pk_mul_f32 v[88:89], v[90:91], v[88:89]
	v_cvt_pk_bf16_f32 v75, v89, v77
	v_cvt_pk_bf16_f32 v74, v88, v76
	v_cvt_pk_bf16_f32 v77, v79, v73
	v_cvt_pk_bf16_f32 v76, v78, v72
	v_lshl_add_u64 v[72:73], s[26:27], 0, v[86:87]
	v_lshl_add_u64 v[72:73], v[72:73], 0, v[138:139]
	global_store_dwordx4 v[72:73], v[74:77], off
	v_mov_b32_e32 v81, v70
	v_mov_b32_e32 v70, v69
	v_mov_b32_e32 v80, v68
	v_lshlrev_b32_e32 v79, 16, v223
	v_lshlrev_b32_e32 v78, 16, v222
	v_and_b32_e32 v75, 0xffff0000, v223
	v_and_b32_e32 v74, 0xffff0000, v222
	v_pk_mul_f32 v[68:69], v[70:71], v[74:75]
	v_lshlrev_b32_e32 v71, 16, v225
	v_lshlrev_b32_e32 v70, 16, v224
	v_mov_b32_e32 v74, v64
	v_mov_b32_e32 v75, v66
	v_pk_mul_f32 v[70:71], v[74:75], v[70:71]
	v_and_b32_e32 v75, 0xffff0000, v225
	v_and_b32_e32 v74, 0xffff0000, v224
	v_mov_b32_e32 v66, v65
	v_pk_mul_f32 v[64:65], v[66:67], v[74:75]
	v_pk_mul_f32 v[78:79], v[80:81], v[78:79]
	v_cvt_pk_bf16_f32 v67, v71, v65
	v_cvt_pk_bf16_f32 v66, v70, v64
	v_cvt_pk_bf16_f32 v65, v79, v69
	v_cvt_pk_bf16_f32 v64, v78, v68
	global_store_dwordx4 v[72:73], v[64:67], off offset:256
	v_mov_b32_e32 v75, v62
	v_mov_b32_e32 v62, v61
	v_add_u32_e32 v64, 0x80, v140
	v_ashrrev_i32_e32 v65, 31, v64
	v_lshlrev_b64 v[66:67], 13, v[64:65]
	v_lshlrev_b64 v[70:71], 12, v[64:65]
	v_lshl_add_u64 v[64:65], s[24:25], 0, v[66:67]
	v_lshl_add_u64 v[64:65], v[64:65], 0, v[138:139]
	v_mov_b32_e32 v74, v60
	s_waitcnt vmcnt(14)
; __device__ __forceinline__ unsigned pk2(float lo, float hi) { return f2bf(lo) | (f2bf(hi) << 16); }
;     __device__ __forceinline__ void operator()(const f32x4 (&acc)[2][2][4][2], const pg8::Unit& u, int wr, int wc, int fr, int fq) const {
;     ...
;                     } else if constexpr (MODE == 2 || MODE == 3) {
;                         const u32x4 g = *(const u32x4*)(aux + row * 4096 + (MODE == 3 ? 2048 : 0) + col);
;                         float r[8] = {v0[0], v0[1], v0[2], v0[3], v1[0], v1[1], v1[2], v1[3]};
;                         const unsigned gw[4] = {g.x, g.y, g.z, g.w};
; #pragma unroll
;                         for (int i = 0; i < 4; ++i) { r[2 * i] *= bf2f(gw[i] & 0xffffu); r[2 * i + 1] *= __builtin_bit_cast(float, gw[i] & 0xffff0000u); }
;                         if constexpr (MODE == 3) { const u32x4 pv = *(const u32x4*)(ob + row * 2048 + col); const unsigned pw[4] = {pv.x, pv.y, pv.z, pv.w};
; #pragma unroll
;                             for (int i = 0; i < 4; ++i) { r[2 * i] += bf2f(pw[i] & 0xffffu); r[2 * i + 1] += __builtin_bit_cast(float, pw[i] & 0xffff0000u); } }
;                         u32x4 w; w.x = pk2(r[0], r[1]); w.y = pk2(r[2], r[3]); w.z = pk2(r[4], r[5]); w.w = pk2(r[6], r[7]);
;                         *(u32x4*)(ob + row * 2048 + col) = w;
	v_lshlrev_b32_e32 v73, 16, v227
	v_lshlrev_b32_e32 v72, 16, v226
	v_and_b32_e32 v67, 0xffff0000, v227
	v_and_b32_e32 v66, 0xffff0000, v226
	v_pk_mul_f32 v[60:61], v[62:63], v[66:67]
	v_lshlrev_b32_e32 v63, 16, v229
	v_lshlrev_b32_e32 v62, 16, v228
	v_mov_b32_e32 v66, v56
	v_mov_b32_e32 v67, v58
	v_pk_mul_f32 v[62:63], v[66:67], v[62:63]
	v_and_b32_e32 v67, 0xffff0000, v229
	v_and_b32_e32 v66, 0xffff0000, v228
	v_mov_b32_e32 v58, v57
	v_pk_mul_f32 v[56:57], v[58:59], v[66:67]
	v_pk_mul_f32 v[72:73], v[74:75], v[72:73]
	v_cvt_pk_bf16_f32 v59, v73, v61
	v_cvt_pk_bf16_f32 v58, v72, v60
	v_cvt_pk_bf16_f32 v61, v63, v57
	v_cvt_pk_bf16_f32 v60, v62, v56
	v_lshl_add_u64 v[56:57], s[26:27], 0, v[70:71]
	v_lshl_add_u64 v[56:57], v[56:57], 0, v[138:139]
	global_store_dwordx4 v[56:57], v[58:61], off
	v_mov_b32_e32 v65, v54
	v_mov_b32_e32 v54, v53
	v_mov_b32_e32 v64, v52
	v_lshlrev_b32_e32 v63, 16, v231
	v_lshlrev_b32_e32 v62, 16, v230
	v_and_b32_e32 v59, 0xffff0000, v231
	v_and_b32_e32 v58, 0xffff0000, v230
	v_pk_mul_f32 v[52:53], v[54:55], v[58:59]
	v_lshlrev_b32_e32 v55, 16, v233
	v_lshlrev_b32_e32 v54, 16, v232
	v_mov_b32_e32 v58, v48
	v_mov_b32_e32 v59, v50
	v_pk_mul_f32 v[54:55], v[58:59], v[54:55]
	v_and_b32_e32 v59, 0xffff0000, v233
	v_and_b32_e32 v58, 0xffff0000, v232
	v_mov_b32_e32 v50, v49
	v_pk_mul_f32 v[48:49], v[50:51], v[58:59]
	v_pk_mul_f32 v[62:63], v[64:65], v[62:63]
	v_cvt_pk_bf16_f32 v51, v55, v49
	v_cvt_pk_bf16_f32 v50, v54, v48
	v_cvt_pk_bf16_f32 v49, v63, v53
	v_cvt_pk_bf16_f32 v48, v62, v52
	global_store_dwordx4 v[56:57], v[48:51], off offset:256
	v_mov_b32_e32 v59, v46
	v_mov_b32_e32 v46, v45
	v_add_u32_e32 v48, 0x90, v140
	v_ashrrev_i32_e32 v49, 31, v48
	v_lshlrev_b64 v[50:51], 13, v[48:49]
	v_lshlrev_b64 v[54:55], 12, v[48:49]
	v_lshl_add_u64 v[48:49], s[24:25], 0, v[50:51]
	v_lshl_add_u64 v[48:49], v[48:49], 0, v[138:139]
	v_mov_b32_e32 v58, v44
	s_waitcnt vmcnt(14)
	v_lshlrev_b32_e32 v57, 16, v235
	v_lshlrev_b32_e32 v56, 16, v234
	v_and_b32_e32 v51, 0xffff0000, v235
	v_and_b32_e32 v50, 0xffff0000, v234
	v_pk_mul_f32 v[44:45], v[46:47], v[50:51]
	v_lshlrev_b32_e32 v47, 16, v237
	v_lshlrev_b32_e32 v46, 16, v236
	v_mov_b32_e32 v50, v40
	v_mov_b32_e32 v51, v42
	v_pk_mul_f32 v[46:47], v[50:51], v[46:47]
	v_and_b32_e32 v51, 0xffff0000, v237
	v_and_b32_e32 v50, 0xffff0000, v236
	v_mov_b32_e32 v42, v41
	v_pk_mul_f32 v[40:41], v[42:43], v[50:51]
	v_pk_mul_f32 v[56:57], v[58:59], v[56:57]
	v_cvt_pk_bf16_f32 v43, v57, v45
	v_cvt_pk_bf16_f32 v42, v56, v44
	v_cvt_pk_bf16_f32 v45, v47, v41
	v_cvt_pk_bf16_f32 v44, v46, v40
	v_lshl_add_u64 v[40:41], s[26:27], 0, v[54:55]
	v_lshl_add_u64 v[40:41], v[40:41], 0, v[138:139]
	global_store_dwordx4 v[40:41], v[42:45], off
	v_mov_b32_e32 v49, v38
	v_mov_b32_e32 v38, v37
	v_mov_b32_e32 v48, v36
	v_lshlrev_b32_e32 v47, 16, v239
	v_lshlrev_b32_e32 v46, 16, v238
	v_and_b32_e32 v43, 0xffff0000, v239
	v_and_b32_e32 v42, 0xffff0000, v238
	v_pk_mul_f32 v[36:37], v[38:39], v[42:43]
	v_lshlrev_b32_e32 v39, 16, v241
	v_lshlrev_b32_e32 v38, 16, v240
	v_mov_b32_e32 v42, v32
	v_mov_b32_e32 v43, v34
	v_pk_mul_f32 v[38:39], v[42:43], v[38:39]
	v_and_b32_e32 v43, 0xffff0000, v241
	v_and_b32_e32 v42, 0xffff0000, v240
	v_mov_b32_e32 v34, v33
	v_pk_mul_f32 v[32:33], v[34:35], v[42:43]
	v_pk_mul_f32 v[46:47], v[48:49], v[46:47]
	v_cvt_pk_bf16_f32 v35, v39, v33
	v_cvt_pk_bf16_f32 v34, v38, v32
	v_cvt_pk_bf16_f32 v33, v47, v37
	v_cvt_pk_bf16_f32 v32, v46, v36
	global_store_dwordx4 v[40:41], v[32:35], off offset:256
	v_mov_b32_e32 v43, v30
	v_mov_b32_e32 v30, v29
	v_add_u32_e32 v32, 0xa0, v140
	v_ashrrev_i32_e32 v33, 31, v32
	v_lshlrev_b64 v[34:35], 13, v[32:33]
	v_lshlrev_b64 v[38:39], 12, v[32:33]
	v_lshl_add_u64 v[32:33], s[24:25], 0, v[34:35]
	v_lshl_add_u64 v[32:33], v[32:33], 0, v[138:139]
	v_mov_b32_e32 v42, v28
	s_waitcnt vmcnt(12)
; #define PG8_BAR __builtin_amdgcn_s_barrier()
; __device__ __forceinline__ unsigned pk2(float lo, float hi) { return f2bf(lo) | (f2bf(hi) << 16); }
; template <class Epi, class Sched, bool ALIGN_EPI = false, bool SP2 = false, bool F8 = false>
; __device__ __forceinline__ void gemm_phase(PG8_LAS unsigned char* lds, const Gemm g, const Sched& S, const Epi& E) {
;     ...
;         cur = nxt; cA = nA; cB = nB; ++ui;
;         if constexpr (ALIGN_EPI) { if (wr == 1) PG8_BAR; }
;     __device__ __forceinline__ void operator()(const f32x4 (&acc)[2][2][4][2], const pg8::Unit& u, int wr, int wc, int fr, int fq) const {
;     ...
;                     } else if constexpr (MODE == 2 || MODE == 3) {
;                         const u32x4 g = *(const u32x4*)(aux + row * 4096 + (MODE == 3 ? 2048 : 0) + col);
;                         float r[8] = {v0[0], v0[1], v0[2], v0[3], v1[0], v1[1], v1[2], v1[3]};
;                         const unsigned gw[4] = {g.x, g.y, g.z, g.w};
; #pragma unroll
;                         for (int i = 0; i < 4; ++i) { r[2 * i] *= bf2f(gw[i] & 0xffffu); r[2 * i + 1] *= __builtin_bit_cast(float, gw[i] & 0xffff0000u); }
;                         if constexpr (MODE == 3) { const u32x4 pv = *(const u32x4*)(ob + row * 2048 + col); const unsigned pw[4] = {pv.x, pv.y, pv.z, pv.w};
; #pragma unroll
;                             for (int i = 0; i < 4; ++i) { r[2 * i] += bf2f(pw[i] & 0xffffu); r[2 * i + 1] += __builtin_bit_cast(float, pw[i] & 0xffff0000u); } }
;                         u32x4 w; w.x = pk2(r[0], r[1]); w.y = pk2(r[2], r[3]); w.z = pk2(r[4], r[5]); w.w = pk2(r[6], r[7]);
;                         *(u32x4*)(ob + row * 2048 + col) = w;
	v_lshlrev_b32_e32 v41, 16, v185
	v_lshlrev_b32_e32 v40, 16, v184
	v_and_b32_e32 v35, 0xffff0000, v185
	v_and_b32_e32 v34, 0xffff0000, v184
	v_pk_mul_f32 v[28:29], v[30:31], v[34:35]
	v_lshlrev_b32_e32 v31, 16, v187
	v_lshlrev_b32_e32 v30, 16, v186
	v_mov_b32_e32 v34, v24
	v_mov_b32_e32 v35, v26
	v_pk_mul_f32 v[30:31], v[34:35], v[30:31]
	v_and_b32_e32 v35, 0xffff0000, v187
	v_and_b32_e32 v34, 0xffff0000, v186
	v_mov_b32_e32 v26, v25
	v_pk_mul_f32 v[24:25], v[26:27], v[34:35]
	v_pk_mul_f32 v[40:41], v[42:43], v[40:41]
	v_cvt_pk_bf16_f32 v27, v41, v29
	v_cvt_pk_bf16_f32 v26, v40, v28
	v_cvt_pk_bf16_f32 v29, v31, v25
	v_cvt_pk_bf16_f32 v28, v30, v24
	v_lshl_add_u64 v[24:25], s[26:27], 0, v[38:39]
	v_lshl_add_u64 v[24:25], v[24:25], 0, v[138:139]
	global_store_dwordx4 v[24:25], v[26:29], off
	v_mov_b32_e32 v33, v22
	v_mov_b32_e32 v22, v21
	v_mov_b32_e32 v32, v20
	v_lshlrev_b32_e32 v31, 16, v189
	v_lshlrev_b32_e32 v30, 16, v188
	v_and_b32_e32 v27, 0xffff0000, v189
	v_and_b32_e32 v26, 0xffff0000, v188
	v_pk_mul_f32 v[20:21], v[22:23], v[26:27]
	v_lshlrev_b32_e32 v23, 16, v191
	v_lshlrev_b32_e32 v22, 16, v190
	v_mov_b32_e32 v26, v16
	v_mov_b32_e32 v27, v18
	v_pk_mul_f32 v[22:23], v[26:27], v[22:23]
	v_and_b32_e32 v27, 0xffff0000, v191
	v_and_b32_e32 v26, 0xffff0000, v190
	v_mov_b32_e32 v18, v17
	v_pk_mul_f32 v[16:17], v[18:19], v[26:27]
	v_pk_mul_f32 v[30:31], v[32:33], v[30:31]
	v_cvt_pk_bf16_f32 v19, v23, v17
	v_cvt_pk_bf16_f32 v18, v22, v16
	v_cvt_pk_bf16_f32 v17, v31, v21
	v_cvt_pk_bf16_f32 v16, v30, v20
	global_store_dwordx4 v[24:25], v[16:19], off offset:256
	v_mov_b32_e32 v27, v14
	v_mov_b32_e32 v14, v13
	v_add_u32_e32 v16, 0xb0, v140
	v_ashrrev_i32_e32 v17, 31, v16
	v_lshlrev_b64 v[18:19], 13, v[16:17]
	v_lshlrev_b64 v[22:23], 12, v[16:17]
	v_lshl_add_u64 v[16:17], s[24:25], 0, v[18:19]
	v_lshl_add_u64 v[16:17], v[16:17], 0, v[138:139]
	v_mov_b32_e32 v26, v12
	s_waitcnt vmcnt(10)
	v_lshlrev_b32_e32 v25, 16, v193
	v_lshlrev_b32_e32 v24, 16, v192
	v_and_b32_e32 v19, 0xffff0000, v193
	v_and_b32_e32 v18, 0xffff0000, v192
	v_pk_mul_f32 v[12:13], v[14:15], v[18:19]
	v_lshlrev_b32_e32 v15, 16, v195
	v_lshlrev_b32_e32 v14, 16, v194
	v_mov_b32_e32 v18, v8
	v_mov_b32_e32 v19, v10
	v_pk_mul_f32 v[14:15], v[18:19], v[14:15]
	v_and_b32_e32 v19, 0xffff0000, v195
	v_and_b32_e32 v18, 0xffff0000, v194
	v_mov_b32_e32 v10, v9
	v_pk_mul_f32 v[8:9], v[10:11], v[18:19]
	v_pk_mul_f32 v[24:25], v[26:27], v[24:25]
	v_cvt_pk_bf16_f32 v11, v25, v13
	v_cvt_pk_bf16_f32 v10, v24, v12
	v_cvt_pk_bf16_f32 v13, v15, v9
	v_cvt_pk_bf16_f32 v12, v14, v8
	v_lshl_add_u64 v[8:9], s[26:27], 0, v[22:23]
	v_lshl_add_u64 v[8:9], v[8:9], 0, v[138:139]
	global_store_dwordx4 v[8:9], v[10:13], off
	v_mov_b32_e32 v17, v6
	v_mov_b32_e32 v6, v5
	v_mov_b32_e32 v16, v4
	v_lshlrev_b32_e32 v15, 16, v197
	v_lshlrev_b32_e32 v14, 16, v196
	v_and_b32_e32 v11, 0xffff0000, v197
	v_and_b32_e32 v10, 0xffff0000, v196
	v_pk_mul_f32 v[4:5], v[6:7], v[10:11]
	v_lshlrev_b32_e32 v7, 16, v199
	v_lshlrev_b32_e32 v6, 16, v198
	v_mov_b32_e32 v10, v0
	v_mov_b32_e32 v11, v2
	v_pk_mul_f32 v[6:7], v[10:11], v[6:7]
	v_and_b32_e32 v11, 0xffff0000, v199
	v_and_b32_e32 v10, 0xffff0000, v198
	v_mov_b32_e32 v2, v1
	v_pk_mul_f32 v[0:1], v[2:3], v[10:11]
	v_pk_mul_f32 v[14:15], v[16:17], v[14:15]
	v_cvt_pk_bf16_f32 v3, v7, v1
	v_cvt_pk_bf16_f32 v2, v6, v0
	v_cvt_pk_bf16_f32 v1, v15, v5
	v_cvt_pk_bf16_f32 v0, v14, v4
	global_store_dwordx4 v[8:9], v[0:3], off offset:256
	s_cbranch_vccnz .LBB0_89
	s_andn2_b64 vcc, exec, s[0:1]
	s_cbranch_vccnz .LBB0_88
	s_barrier
	s_branch .LBB0_88

; __device__ __forceinline__ unsigned pk2(float lo, float hi) { return f2bf(lo) | (f2bf(hi) << 16); }
;     __device__ __forceinline__ void operator()(const f32x4 (&acc)[2][2][4][2], const pg8::Unit& u, int wr, int wc, int fr, int fq) const {
;     ...
;                     } else if constexpr (MODE == 2 || MODE == 3) {
;                         const u32x4 g = *(const u32x4*)(aux + row * 4096 + (MODE == 3 ? 2048 : 0) + col);
;                         float r[8] = {v0[0], v0[1], v0[2], v0[3], v1[0], v1[1], v1[2], v1[3]};
;                         const unsigned gw[4] = {g.x, g.y, g.z, g.w};
; #pragma unroll
;                         for (int i = 0; i < 4; ++i) { r[2 * i] *= bf2f(gw[i] & 0xffffu); r[2 * i + 1] *= __builtin_bit_cast(float, gw[i] & 0xffff0000u); }
;                         if constexpr (MODE == 3) { const u32x4 pv = *(const u32x4*)(ob + row * 2048 + col); const unsigned pw[4] = {pv.x, pv.y, pv.z, pv.w};
; #pragma unroll
;                             for (int i = 0; i < 4; ++i) { r[2 * i] += bf2f(pw[i] & 0xffffu); r[2 * i + 1] += __builtin_bit_cast(float, pw[i] & 0xffff0000u); } }
;                         u32x4 w; w.x = pk2(r[0], r[1]); w.y = pk2(r[2], r[3]); w.z = pk2(r[4], r[5]); w.w = pk2(r[6], r[7]);
;                         *(u32x4*)(ob + row * 2048 + col) = w;
.LBB0_120:
	v_lshl_add_u32 v140, s9, 8, v144
	v_ashrrev_i32_e32 v141, 31, v140
	v_lshl_or_b32 v156, s8, 8, v146
	v_lshlrev_b64 v[138:139], 13, v[140:141]
	v_lshlrev_b64 v[142:143], 12, v[140:141]
	v_lshl_add_u64 v[138:139], s[24:25], 0, v[138:139]
	s_mov_b64 s[8:9], 0x1000
	v_ashrrev_i32_e32 v157, 31, v156
	v_lshl_add_u64 v[158:159], v[138:139], 0, s[8:9]
	v_lshlrev_b64 v[138:139], 1, v[156:157]
	v_lshl_add_u64 v[142:143], s[26:27], 0, v[142:143]
	v_lshl_add_u64 v[148:149], v[158:159], 0, v[138:139]
	v_lshl_add_u64 v[142:143], v[142:143], 0, v[138:139]
	global_load_dwordx4 v[200:203], v[148:149], off
	global_load_dwordx4 v[214:217], v[142:143], off
	v_or_b32_e32 v186, 0x80, v156
	v_ashrrev_i32_e32 v187, 31, v186
	v_lshlrev_b64 v[188:189], 1, v[186:187]
	v_lshl_add_u64 v[186:187], v[158:159], 0, v[188:189]
	global_load_dwordx4 v[218:221], v[186:187], off
	global_load_dwordx4 v[222:225], v[142:143], off offset:256
	v_or_b32_e32 v186, 16, v140
	v_ashrrev_i32_e32 v187, 31, v186
	v_lshlrev_b64 v[188:189], 13, v[186:187]
	v_lshl_add_u64 v[188:189], s[24:25], 0, v[188:189]
	v_lshl_add_u64 v[188:189], v[188:189], 0, s[8:9]
	v_lshl_add_u64 v[190:191], v[188:189], 0, v[138:139]
	global_load_dwordx4 v[226:229], v[190:191], off
	v_or_b32_e32 v186, 16, v140
	v_ashrrev_i32_e32 v187, 31, v186
	v_lshlrev_b64 v[186:187], 12, v[186:187]
	v_lshl_add_u64 v[186:187], s[26:27], 0, v[186:187]
	v_lshl_add_u64 v[186:187], v[186:187], 0, v[138:139]
	global_load_dwordx4 v[230:233], v[186:187], off
	v_or_b32_e32 v186, 0x80, v156
	v_ashrrev_i32_e32 v187, 31, v186
	v_lshlrev_b64 v[188:189], 1, v[186:187]
	v_or_b32_e32 v190, 16, v140
	v_ashrrev_i32_e32 v191, 31, v190
	v_lshlrev_b64 v[192:193], 13, v[190:191]
	v_lshl_add_u64 v[192:193], s[24:25], 0, v[192:193]
	v_lshl_add_u64 v[192:193], v[192:193], 0, s[8:9]
	v_lshl_add_u64 v[194:195], v[192:193], 0, v[188:189]
	global_load_dwordx4 v[234:237], v[194:195], off
	v_or_b32_e32 v186, 16, v140
	v_ashrrev_i32_e32 v187, 31, v186
	v_lshlrev_b64 v[186:187], 12, v[186:187]
	v_lshl_add_u64 v[186:187], s[26:27], 0, v[186:187]
	v_lshl_add_u64 v[186:187], v[186:187], 0, v[138:139]
	global_load_dwordx4 v[238:241], v[186:187], off offset:256
	v_mov_b32_e32 v184, v124
	v_mov_b32_e32 v185, v126
	v_mov_b32_e32 v126, v125
	s_mov_b64 s[10:11], -1
	s_andn2_b64 vcc, exec, s[38:39]
	s_waitcnt vmcnt(4)
	v_lshlrev_b32_e32 v163, 16, v201
	v_lshlrev_b32_e32 v162, 16, v200
	v_and_b32_e32 v149, 0xffff0000, v201
	v_and_b32_e32 v148, 0xffff0000, v200
	v_lshlrev_b32_e32 v125, 16, v215
	v_lshlrev_b32_e32 v124, 16, v214
	v_and_b32_e32 v153, 0xffff0000, v215
	v_and_b32_e32 v152, 0xffff0000, v214
	v_pk_fma_f32 v[126:127], v[126:127], v[148:149], v[152:153]
	v_lshlrev_b32_e32 v149, 16, v203
	v_lshlrev_b32_e32 v148, 16, v202
	v_mov_b32_e32 v152, v120
	v_mov_b32_e32 v153, v122
	v_mov_b32_e32 v122, v121
	v_lshlrev_b32_e32 v121, 16, v217
	v_lshlrev_b32_e32 v120, 16, v216
	v_and_b32_e32 v151, 0xffff0000, v203
	v_and_b32_e32 v150, 0xffff0000, v202
	v_pk_fma_f32 v[120:121], v[152:153], v[148:149], v[120:121]
	v_and_b32_e32 v149, 0xffff0000, v217
	v_and_b32_e32 v148, 0xffff0000, v216
	v_pk_fma_f32 v[122:123], v[122:123], v[150:151], v[148:149]
	v_pk_fma_f32 v[124:125], v[184:185], v[162:163], v[124:125]
	v_cvt_pk_bf16_f32 v123, v121, v123
	v_cvt_pk_bf16_f32 v122, v120, v122
	v_cvt_pk_bf16_f32 v121, v125, v127
	v_cvt_pk_bf16_f32 v120, v124, v126
	global_store_dwordx4 v[142:143], v[120:123], off
	v_mov_b32_e32 v152, v116
	v_mov_b32_e32 v153, v118
	v_or_b32_e32 v120, 0x80, v156
	v_ashrrev_i32_e32 v121, 31, v120
	v_lshlrev_b64 v[124:125], 1, v[120:121]
	v_lshl_add_u64 v[120:121], v[158:159], 0, v[124:125]
	s_nop 0
	v_mov_b32_e32 v118, v117
	v_lshlrev_b32_e32 v127, 16, v219
	v_lshlrev_b32_e32 v126, 16, v218
	v_lshlrev_b32_e32 v117, 16, v223
	v_lshlrev_b32_e32 v116, 16, v222
	v_and_b32_e32 v121, 0xffff0000, v219
	v_and_b32_e32 v120, 0xffff0000, v218
	v_pk_fma_f32 v[116:117], v[152:153], v[126:127], v[116:117]
	v_and_b32_e32 v127, 0xffff0000, v223
	v_and_b32_e32 v126, 0xffff0000, v222
	v_pk_fma_f32 v[118:119], v[118:119], v[120:121], v[126:127]
	v_lshlrev_b32_e32 v121, 16, v221
	v_lshlrev_b32_e32 v120, 16, v220
	v_mov_b32_e32 v126, v112
	v_mov_b32_e32 v127, v114
	v_mov_b32_e32 v114, v113
	v_lshlrev_b32_e32 v113, 16, v225
	v_lshlrev_b32_e32 v112, 16, v224
	v_and_b32_e32 v123, 0xffff0000, v221
	v_and_b32_e32 v122, 0xffff0000, v220
	v_pk_fma_f32 v[112:113], v[126:127], v[120:121], v[112:113]
	v_and_b32_e32 v121, 0xffff0000, v225
	v_and_b32_e32 v120, 0xffff0000, v224
	v_pk_fma_f32 v[114:115], v[114:115], v[122:123], v[120:121]
	v_cvt_pk_bf16_f32 v115, v113, v115
	v_cvt_pk_bf16_f32 v114, v112, v114
	v_cvt_pk_bf16_f32 v113, v117, v119
	v_cvt_pk_bf16_f32 v112, v116, v118
	global_store_dwordx4 v[142:143], v[112:115], off offset:256
	v_mov_b32_e32 v142, v108
	v_mov_b32_e32 v143, v110
	v_or_b32_e32 v112, 16, v140
	v_ashrrev_i32_e32 v113, 31, v112
	v_lshlrev_b64 v[114:115], 13, v[112:113]
	v_lshlrev_b64 v[112:113], 12, v[112:113]
	v_lshl_add_u64 v[114:115], s[24:25], 0, v[114:115]
	v_lshl_add_u64 v[114:115], v[114:115], 0, s[8:9]
	v_lshl_add_u64 v[112:113], s[26:27], 0, v[112:113]
	v_lshl_add_u64 v[116:117], v[114:115], 0, v[138:139]
	v_lshl_add_u64 v[112:113], v[112:113], 0, v[138:139]
	v_or_b32_e32 v186, 32, v140
	v_ashrrev_i32_e32 v187, 31, v186
	v_lshlrev_b64 v[188:189], 13, v[186:187]
	v_lshl_add_u64 v[188:189], s[24:25], 0, v[188:189]
	v_lshl_add_u64 v[188:189], v[188:189], 0, s[8:9]
	v_lshl_add_u64 v[190:191], v[188:189], 0, v[138:139]
	global_load_dwordx4 v[200:203], v[190:191], off
	v_or_b32_e32 v186, 32, v140
	v_ashrrev_i32_e32 v187, 31, v186
	v_lshlrev_b64 v[186:187], 12, v[186:187]
	v_lshl_add_u64 v[186:187], s[26:27], 0, v[186:187]
	v_lshl_add_u64 v[186:187], v[186:187], 0, v[138:139]
	global_load_dwordx4 v[214:217], v[186:187], off
	v_or_b32_e32 v186, 0x80, v156
	v_ashrrev_i32_e32 v187, 31, v186
	v_lshlrev_b64 v[188:189], 1, v[186:187]
	v_or_b32_e32 v190, 32, v140
	v_ashrrev_i32_e32 v191, 31, v190
	v_lshlrev_b64 v[192:193], 13, v[190:191]
	v_lshl_add_u64 v[192:193], s[24:25], 0, v[192:193]
	v_lshl_add_u64 v[192:193], v[192:193], 0, s[8:9]
	v_lshl_add_u64 v[194:195], v[192:193], 0, v[188:189]
	global_load_dwordx4 v[218:221], v[194:195], off
	v_or_b32_e32 v186, 32, v140
	v_ashrrev_i32_e32 v187, 31, v186
	v_lshlrev_b64 v[186:187], 12, v[186:187]
	v_lshl_add_u64 v[186:187], s[26:27], 0, v[186:187]
	v_lshl_add_u64 v[186:187], v[186:187], 0, v[138:139]
	global_load_dwordx4 v[222:225], v[186:187], off offset:256
	v_mov_b32_e32 v110, v109
	s_waitcnt vmcnt(6)
; __device__ __forceinline__ unsigned pk2(float lo, float hi) { return f2bf(lo) | (f2bf(hi) << 16); }
;     __device__ __forceinline__ void operator()(const f32x4 (&acc)[2][2][4][2], const pg8::Unit& u, int wr, int wc, int fr, int fq) const {
;     ...
;                     } else if constexpr (MODE == 2 || MODE == 3) {
;                         const u32x4 g = *(const u32x4*)(aux + row * 4096 + (MODE == 3 ? 2048 : 0) + col);
;                         float r[8] = {v0[0], v0[1], v0[2], v0[3], v1[0], v1[1], v1[2], v1[3]};
;                         const unsigned gw[4] = {g.x, g.y, g.z, g.w};
; #pragma unroll
;                         for (int i = 0; i < 4; ++i) { r[2 * i] *= bf2f(gw[i] & 0xffffu); r[2 * i + 1] *= __builtin_bit_cast(float, gw[i] & 0xffff0000u); }
;                         if constexpr (MODE == 3) { const u32x4 pv = *(const u32x4*)(ob + row * 2048 + col); const unsigned pw[4] = {pv.x, pv.y, pv.z, pv.w};
; #pragma unroll
;                             for (int i = 0; i < 4; ++i) { r[2 * i] += bf2f(pw[i] & 0xffffu); r[2 * i + 1] += __builtin_bit_cast(float, pw[i] & 0xffff0000u); } }
;                         u32x4 w; w.x = pk2(r[0], r[1]); w.y = pk2(r[2], r[3]); w.z = pk2(r[4], r[5]); w.w = pk2(r[6], r[7]);
;                         *(u32x4*)(ob + row * 2048 + col) = w;
	v_lshlrev_b32_e32 v127, 16, v227
	v_lshlrev_b32_e32 v126, 16, v226
	v_and_b32_e32 v117, 0xffff0000, v227
	v_and_b32_e32 v116, 0xffff0000, v226
	v_lshlrev_b32_e32 v109, 16, v231
	v_lshlrev_b32_e32 v108, 16, v230
	v_and_b32_e32 v121, 0xffff0000, v231
	v_and_b32_e32 v120, 0xffff0000, v230
	v_pk_fma_f32 v[110:111], v[110:111], v[116:117], v[120:121]
	v_lshlrev_b32_e32 v117, 16, v229
	v_lshlrev_b32_e32 v116, 16, v228
	v_mov_b32_e32 v120, v104
	v_mov_b32_e32 v121, v106
	v_mov_b32_e32 v106, v105
	v_lshlrev_b32_e32 v105, 16, v233
	v_lshlrev_b32_e32 v104, 16, v232
	v_and_b32_e32 v119, 0xffff0000, v229
	v_and_b32_e32 v118, 0xffff0000, v228
	v_pk_fma_f32 v[104:105], v[120:121], v[116:117], v[104:105]
	v_and_b32_e32 v117, 0xffff0000, v233
	v_and_b32_e32 v116, 0xffff0000, v232
	v_pk_fma_f32 v[106:107], v[106:107], v[118:119], v[116:117]
	v_pk_fma_f32 v[108:109], v[142:143], v[126:127], v[108:109]
	v_cvt_pk_bf16_f32 v107, v105, v107
	v_cvt_pk_bf16_f32 v106, v104, v106
	v_cvt_pk_bf16_f32 v105, v109, v111
	v_cvt_pk_bf16_f32 v104, v108, v110
	global_store_dwordx4 v[112:113], v[104:107], off
	v_mov_b32_e32 v116, v100
	v_mov_b32_e32 v117, v102
	v_lshl_add_u64 v[104:105], v[114:115], 0, v[124:125]
	s_nop 0
	v_mov_b32_e32 v102, v101
	v_lshlrev_b32_e32 v115, 16, v235
	v_lshlrev_b32_e32 v114, 16, v234
	v_and_b32_e32 v105, 0xffff0000, v235
	v_and_b32_e32 v104, 0xffff0000, v234
	v_lshlrev_b32_e32 v101, 16, v239
	v_lshlrev_b32_e32 v100, 16, v238
	v_and_b32_e32 v109, 0xffff0000, v239
	v_and_b32_e32 v108, 0xffff0000, v238
	v_pk_fma_f32 v[102:103], v[102:103], v[104:105], v[108:109]
	v_lshlrev_b32_e32 v105, 16, v237
	v_lshlrev_b32_e32 v104, 16, v236
	v_mov_b32_e32 v108, v96
	v_mov_b32_e32 v109, v98
	v_mov_b32_e32 v98, v97
	v_lshlrev_b32_e32 v97, 16, v241
	v_lshlrev_b32_e32 v96, 16, v240
	v_and_b32_e32 v107, 0xffff0000, v237
	v_and_b32_e32 v106, 0xffff0000, v236
	v_pk_fma_f32 v[96:97], v[108:109], v[104:105], v[96:97]
	v_and_b32_e32 v105, 0xffff0000, v241
	v_and_b32_e32 v104, 0xffff0000, v240
	v_pk_fma_f32 v[98:99], v[98:99], v[106:107], v[104:105]
	v_pk_fma_f32 v[100:101], v[116:117], v[114:115], v[100:101]
	v_cvt_pk_bf16_f32 v99, v97, v99
	v_cvt_pk_bf16_f32 v98, v96, v98
	v_cvt_pk_bf16_f32 v97, v101, v103
	v_cvt_pk_bf16_f32 v96, v100, v102
	global_store_dwordx4 v[112:113], v[96:99], off offset:256
	v_mov_b32_e32 v110, v92
	v_mov_b32_e32 v111, v94
	v_or_b32_e32 v96, 32, v140
	v_ashrrev_i32_e32 v97, 31, v96
	v_lshlrev_b64 v[98:99], 13, v[96:97]
	v_lshlrev_b64 v[96:97], 12, v[96:97]
	v_lshl_add_u64 v[98:99], s[24:25], 0, v[98:99]
	v_lshl_add_u64 v[98:99], v[98:99], 0, s[8:9]
	v_lshl_add_u64 v[96:97], s[26:27], 0, v[96:97]
	v_lshl_add_u64 v[100:101], v[98:99], 0, v[138:139]
	v_lshl_add_u64 v[96:97], v[96:97], 0, v[138:139]
	v_or_b32_e32 v186, 48, v140
	v_ashrrev_i32_e32 v187, 31, v186
	v_lshlrev_b64 v[188:189], 13, v[186:187]
	v_lshl_add_u64 v[188:189], s[24:25], 0, v[188:189]
	v_lshl_add_u64 v[188:189], v[188:189], 0, s[8:9]
	v_lshl_add_u64 v[190:191], v[188:189], 0, v[138:139]
	global_load_dwordx4 v[226:229], v[190:191], off
	v_or_b32_e32 v186, 48, v140
	v_ashrrev_i32_e32 v187, 31, v186
	v_lshlrev_b64 v[186:187], 12, v[186:187]
	v_lshl_add_u64 v[186:187], s[26:27], 0, v[186:187]
	v_lshl_add_u64 v[186:187], v[186:187], 0, v[138:139]
	global_load_dwordx4 v[230:233], v[186:187], off
	v_or_b32_e32 v186, 0x80, v156
	v_ashrrev_i32_e32 v187, 31, v186
	v_lshlrev_b64 v[188:189], 1, v[186:187]
	v_or_b32_e32 v190, 48, v140
	v_ashrrev_i32_e32 v191, 31, v190
	v_lshlrev_b64 v[192:193], 13, v[190:191]
	v_lshl_add_u64 v[192:193], s[24:25], 0, v[192:193]
	v_lshl_add_u64 v[192:193], v[192:193], 0, s[8:9]
	v_lshl_add_u64 v[194:195], v[192:193], 0, v[188:189]
	global_load_dwordx4 v[234:237], v[194:195], off
	v_or_b32_e32 v186, 48, v140
	v_ashrrev_i32_e32 v187, 31, v186
	v_lshlrev_b64 v[186:187], 12, v[186:187]
	v_lshl_add_u64 v[186:187], s[26:27], 0, v[186:187]
	v_lshl_add_u64 v[186:187], v[186:187], 0, v[138:139]
	global_load_dwordx4 v[238:241], v[186:187], off offset:256
	v_mov_b32_e32 v94, v93
	s_waitcnt vmcnt(6)
	v_lshlrev_b32_e32 v109, 16, v201
	v_lshlrev_b32_e32 v108, 16, v200
	v_and_b32_e32 v101, 0xffff0000, v201
	v_and_b32_e32 v100, 0xffff0000, v200
	v_lshlrev_b32_e32 v93, 16, v215
	v_lshlrev_b32_e32 v92, 16, v214
	v_and_b32_e32 v105, 0xffff0000, v215
	v_and_b32_e32 v104, 0xffff0000, v214
	v_pk_fma_f32 v[94:95], v[94:95], v[100:101], v[104:105]
	v_lshlrev_b32_e32 v101, 16, v203
	v_lshlrev_b32_e32 v100, 16, v202
	v_mov_b32_e32 v104, v88
	v_mov_b32_e32 v105, v90
	v_mov_b32_e32 v90, v89
	v_lshlrev_b32_e32 v89, 16, v217
	v_lshlrev_b32_e32 v88, 16, v216
	v_and_b32_e32 v103, 0xffff0000, v203
	v_and_b32_e32 v102, 0xffff0000, v202
	v_pk_fma_f32 v[88:89], v[104:105], v[100:101], v[88:89]
	v_and_b32_e32 v101, 0xffff0000, v217
	v_and_b32_e32 v100, 0xffff0000, v216
	v_pk_fma_f32 v[90:91], v[90:91], v[102:103], v[100:101]
	v_pk_fma_f32 v[92:93], v[110:111], v[108:109], v[92:93]
	v_cvt_pk_bf16_f32 v91, v89, v91
	v_cvt_pk_bf16_f32 v90, v88, v90
	v_cvt_pk_bf16_f32 v89, v93, v95
	v_cvt_pk_bf16_f32 v88, v92, v94
	global_store_dwordx4 v[96:97], v[88:91], off
	v_mov_b32_e32 v100, v84
	v_mov_b32_e32 v101, v86
	v_lshl_add_u64 v[88:89], v[98:99], 0, v[124:125]
	s_nop 0
	v_mov_b32_e32 v86, v85
	v_lshlrev_b32_e32 v99, 16, v219
	v_lshlrev_b32_e32 v98, 16, v218
	v_and_b32_e32 v89, 0xffff0000, v219
	v_and_b32_e32 v88, 0xffff0000, v218
	v_lshlrev_b32_e32 v85, 16, v223
	v_lshlrev_b32_e32 v84, 16, v222
	v_and_b32_e32 v93, 0xffff0000, v223
	v_and_b32_e32 v92, 0xffff0000, v222
	v_pk_fma_f32 v[86:87], v[86:87], v[88:89], v[92:93]
	v_lshlrev_b32_e32 v89, 16, v221
	v_lshlrev_b32_e32 v88, 16, v220
	v_mov_b32_e32 v92, v80
; __device__ __forceinline__ unsigned pk2(float lo, float hi) { return f2bf(lo) | (f2bf(hi) << 16); }
;     __device__ __forceinline__ void operator()(const f32x4 (&acc)[2][2][4][2], const pg8::Unit& u, int wr, int wc, int fr, int fq) const {
;     ...
;                     } else if constexpr (MODE == 2 || MODE == 3) {
;                         const u32x4 g = *(const u32x4*)(aux + row * 4096 + (MODE == 3 ? 2048 : 0) + col);
;                         float r[8] = {v0[0], v0[1], v0[2], v0[3], v1[0], v1[1], v1[2], v1[3]};
;                         const unsigned gw[4] = {g.x, g.y, g.z, g.w};
; #pragma unroll
;                         for (int i = 0; i < 4; ++i) { r[2 * i] *= bf2f(gw[i] & 0xffffu); r[2 * i + 1] *= __builtin_bit_cast(float, gw[i] & 0xffff0000u); }
;                         if constexpr (MODE == 3) { const u32x4 pv = *(const u32x4*)(ob + row * 2048 + col); const unsigned pw[4] = {pv.x, pv.y, pv.z, pv.w};
; #pragma unroll
;                             for (int i = 0; i < 4; ++i) { r[2 * i] += bf2f(pw[i] & 0xffffu); r[2 * i + 1] += __builtin_bit_cast(float, pw[i] & 0xffff0000u); } }
;                         u32x4 w; w.x = pk2(r[0], r[1]); w.y = pk2(r[2], r[3]); w.z = pk2(r[4], r[5]); w.w = pk2(r[6], r[7]);
;                         *(u32x4*)(ob + row * 2048 + col) = w;
	v_mov_b32_e32 v93, v82
	v_mov_b32_e32 v82, v81
	v_lshlrev_b32_e32 v81, 16, v225
	v_lshlrev_b32_e32 v80, 16, v224
	v_and_b32_e32 v91, 0xffff0000, v221
	v_and_b32_e32 v90, 0xffff0000, v220
	v_pk_fma_f32 v[80:81], v[92:93], v[88:89], v[80:81]
	v_and_b32_e32 v89, 0xffff0000, v225
	v_and_b32_e32 v88, 0xffff0000, v224
	v_pk_fma_f32 v[82:83], v[82:83], v[90:91], v[88:89]
	v_pk_fma_f32 v[84:85], v[100:101], v[98:99], v[84:85]
	v_cvt_pk_bf16_f32 v83, v81, v83
	v_cvt_pk_bf16_f32 v82, v80, v82
	v_cvt_pk_bf16_f32 v81, v85, v87
	v_cvt_pk_bf16_f32 v80, v84, v86
	global_store_dwordx4 v[96:97], v[80:83], off offset:256
	v_mov_b32_e32 v94, v76
	v_mov_b32_e32 v95, v78
	v_or_b32_e32 v80, 48, v140
	v_ashrrev_i32_e32 v81, 31, v80
	v_lshlrev_b64 v[82:83], 13, v[80:81]
	v_lshlrev_b64 v[80:81], 12, v[80:81]
	v_lshl_add_u64 v[82:83], s[24:25], 0, v[82:83]
	v_lshl_add_u64 v[82:83], v[82:83], 0, s[8:9]
	v_lshl_add_u64 v[80:81], s[26:27], 0, v[80:81]
	v_lshl_add_u64 v[84:85], v[82:83], 0, v[138:139]
	v_lshl_add_u64 v[80:81], v[80:81], 0, v[138:139]
	v_add_u32_e32 v186, 0x80, v140
	v_ashrrev_i32_e32 v187, 31, v186
	v_lshlrev_b64 v[188:189], 13, v[186:187]
	v_lshl_add_u64 v[188:189], s[24:25], 0, v[188:189]
	v_lshl_add_u64 v[188:189], v[188:189], 0, s[8:9]
	v_lshl_add_u64 v[190:191], v[188:189], 0, v[138:139]
	global_load_dwordx4 v[200:203], v[190:191], off
	v_add_u32_e32 v186, 0x80, v140
	v_ashrrev_i32_e32 v187, 31, v186
	v_lshlrev_b64 v[186:187], 12, v[186:187]
	v_lshl_add_u64 v[186:187], s[26:27], 0, v[186:187]
	v_lshl_add_u64 v[186:187], v[186:187], 0, v[138:139]
	global_load_dwordx4 v[214:217], v[186:187], off
	v_or_b32_e32 v186, 0x80, v156
	v_ashrrev_i32_e32 v187, 31, v186
	v_lshlrev_b64 v[188:189], 1, v[186:187]
	v_add_u32_e32 v190, 0x80, v140
	v_ashrrev_i32_e32 v191, 31, v190
	v_lshlrev_b64 v[192:193], 13, v[190:191]
	v_lshl_add_u64 v[192:193], s[24:25], 0, v[192:193]
	v_lshl_add_u64 v[192:193], v[192:193], 0, s[8:9]
	v_lshl_add_u64 v[194:195], v[192:193], 0, v[188:189]
	global_load_dwordx4 v[218:221], v[194:195], off
	v_add_u32_e32 v186, 0x80, v140
	v_ashrrev_i32_e32 v187, 31, v186
	v_lshlrev_b64 v[186:187], 12, v[186:187]
	v_lshl_add_u64 v[186:187], s[26:27], 0, v[186:187]
	v_lshl_add_u64 v[186:187], v[186:187], 0, v[138:139]
	global_load_dwordx4 v[222:225], v[186:187], off offset:256
	v_mov_b32_e32 v78, v77
	s_waitcnt vmcnt(6)
	v_lshlrev_b32_e32 v93, 16, v227
	v_lshlrev_b32_e32 v92, 16, v226
	v_and_b32_e32 v85, 0xffff0000, v227
	v_and_b32_e32 v84, 0xffff0000, v226
	v_lshlrev_b32_e32 v77, 16, v231
	v_lshlrev_b32_e32 v76, 16, v230
	v_and_b32_e32 v89, 0xffff0000, v231
	v_and_b32_e32 v88, 0xffff0000, v230
	v_pk_fma_f32 v[78:79], v[78:79], v[84:85], v[88:89]
	v_lshlrev_b32_e32 v85, 16, v229
	v_lshlrev_b32_e32 v84, 16, v228
	v_mov_b32_e32 v88, v72
	v_mov_b32_e32 v89, v74
	v_mov_b32_e32 v74, v73
	v_lshlrev_b32_e32 v73, 16, v233
	v_lshlrev_b32_e32 v72, 16, v232
	v_and_b32_e32 v87, 0xffff0000, v229
	v_and_b32_e32 v86, 0xffff0000, v228
	v_pk_fma_f32 v[72:73], v[88:89], v[84:85], v[72:73]
	v_and_b32_e32 v85, 0xffff0000, v233
	v_and_b32_e32 v84, 0xffff0000, v232
	v_pk_fma_f32 v[74:75], v[74:75], v[86:87], v[84:85]
	v_pk_fma_f32 v[76:77], v[94:95], v[92:93], v[76:77]
	v_cvt_pk_bf16_f32 v75, v73, v75
	v_cvt_pk_bf16_f32 v74, v72, v74
	v_cvt_pk_bf16_f32 v73, v77, v79
	v_cvt_pk_bf16_f32 v72, v76, v78
	global_store_dwordx4 v[80:81], v[72:75], off
	v_mov_b32_e32 v84, v68
	v_mov_b32_e32 v85, v70
	v_lshl_add_u64 v[72:73], v[82:83], 0, v[124:125]
	s_nop 0
	v_mov_b32_e32 v70, v69
	v_lshlrev_b32_e32 v83, 16, v235
	v_lshlrev_b32_e32 v82, 16, v234
	v_and_b32_e32 v73, 0xffff0000, v235
	v_and_b32_e32 v72, 0xffff0000, v234
	v_lshlrev_b32_e32 v69, 16, v239
	v_lshlrev_b32_e32 v68, 16, v238
	v_and_b32_e32 v77, 0xffff0000, v239
	v_and_b32_e32 v76, 0xffff0000, v238
	v_pk_fma_f32 v[70:71], v[70:71], v[72:73], v[76:77]
	v_lshlrev_b32_e32 v73, 16, v237
	v_lshlrev_b32_e32 v72, 16, v236
	v_mov_b32_e32 v76, v64
	v_mov_b32_e32 v77, v66
	v_mov_b32_e32 v66, v65
	v_lshlrev_b32_e32 v65, 16, v241
	v_lshlrev_b32_e32 v64, 16, v240
	v_and_b32_e32 v75, 0xffff0000, v237
	v_and_b32_e32 v74, 0xffff0000, v236
	v_pk_fma_f32 v[64:65], v[76:77], v[72:73], v[64:65]
	v_and_b32_e32 v73, 0xffff0000, v241
	v_and_b32_e32 v72, 0xffff0000, v240
	v_pk_fma_f32 v[66:67], v[66:67], v[74:75], v[72:73]
	v_pk_fma_f32 v[68:69], v[84:85], v[82:83], v[68:69]
	v_cvt_pk_bf16_f32 v67, v65, v67
	v_cvt_pk_bf16_f32 v66, v64, v66
	v_cvt_pk_bf16_f32 v65, v69, v71
	v_cvt_pk_bf16_f32 v64, v68, v70
	global_store_dwordx4 v[80:81], v[64:67], off offset:256
	v_mov_b32_e32 v78, v60
	v_mov_b32_e32 v79, v62
	v_add_u32_e32 v64, 0x80, v140
	v_ashrrev_i32_e32 v65, 31, v64
	v_lshlrev_b64 v[66:67], 13, v[64:65]
	v_lshlrev_b64 v[64:65], 12, v[64:65]
	v_lshl_add_u64 v[66:67], s[24:25], 0, v[66:67]
	v_lshl_add_u64 v[66:67], v[66:67], 0, s[8:9]
	v_lshl_add_u64 v[64:65], s[26:27], 0, v[64:65]
	v_lshl_add_u64 v[68:69], v[66:67], 0, v[138:139]
	v_lshl_add_u64 v[64:65], v[64:65], 0, v[138:139]
	v_add_u32_e32 v186, 0x90, v140
	v_ashrrev_i32_e32 v187, 31, v186
	v_lshlrev_b64 v[188:189], 13, v[186:187]
	v_lshl_add_u64 v[188:189], s[24:25], 0, v[188:189]
	v_lshl_add_u64 v[188:189], v[188:189], 0, s[8:9]
	v_lshl_add_u64 v[190:191], v[188:189], 0, v[138:139]
	global_load_dwordx4 v[226:229], v[190:191], off
	v_add_u32_e32 v186, 0x90, v140
	v_ashrrev_i32_e32 v187, 31, v186
	v_lshlrev_b64 v[186:187], 12, v[186:187]
	v_lshl_add_u64 v[186:187], s[26:27], 0, v[186:187]
	v_lshl_add_u64 v[186:187], v[186:187], 0, v[138:139]
	global_load_dwordx4 v[230:233], v[186:187], off
	v_or_b32_e32 v186, 0x80, v156
	v_ashrrev_i32_e32 v187, 31, v186
	v_lshlrev_b64 v[188:189], 1, v[186:187]
	v_add_u32_e32 v190, 0x90, v140
	v_ashrrev_i32_e32 v191, 31, v190
	v_lshlrev_b64 v[192:193], 13, v[190:191]
	v_lshl_add_u64 v[192:193], s[24:25], 0, v[192:193]
	v_lshl_add_u64 v[192:193], v[192:193], 0, s[8:9]
	v_lshl_add_u64 v[194:195], v[192:193], 0, v[188:189]
	global_load_dwordx4 v[234:237], v[194:195], off
	v_add_u32_e32 v186, 0x90, v140
	v_ashrrev_i32_e32 v187, 31, v186
	v_lshlrev_b64 v[186:187], 12, v[186:187]
	v_lshl_add_u64 v[186:187], s[26:27], 0, v[186:187]
	v_lshl_add_u64 v[186:187], v[186:187], 0, v[138:139]
	global_load_dwordx4 v[238:241], v[186:187], off offset:256
	v_mov_b32_e32 v62, v61
	s_waitcnt vmcnt(6)
; __device__ __forceinline__ unsigned pk2(float lo, float hi) { return f2bf(lo) | (f2bf(hi) << 16); }
;     __device__ __forceinline__ void operator()(const f32x4 (&acc)[2][2][4][2], const pg8::Unit& u, int wr, int wc, int fr, int fq) const {
;     ...
;                     } else if constexpr (MODE == 2 || MODE == 3) {
;                         const u32x4 g = *(const u32x4*)(aux + row * 4096 + (MODE == 3 ? 2048 : 0) + col);
;                         float r[8] = {v0[0], v0[1], v0[2], v0[3], v1[0], v1[1], v1[2], v1[3]};
;                         const unsigned gw[4] = {g.x, g.y, g.z, g.w};
; #pragma unroll
;                         for (int i = 0; i < 4; ++i) { r[2 * i] *= bf2f(gw[i] & 0xffffu); r[2 * i + 1] *= __builtin_bit_cast(float, gw[i] & 0xffff0000u); }
;                         if constexpr (MODE == 3) { const u32x4 pv = *(const u32x4*)(ob + row * 2048 + col); const unsigned pw[4] = {pv.x, pv.y, pv.z, pv.w};
; #pragma unroll
;                             for (int i = 0; i < 4; ++i) { r[2 * i] += bf2f(pw[i] & 0xffffu); r[2 * i + 1] += __builtin_bit_cast(float, pw[i] & 0xffff0000u); } }
;                         u32x4 w; w.x = pk2(r[0], r[1]); w.y = pk2(r[2], r[3]); w.z = pk2(r[4], r[5]); w.w = pk2(r[6], r[7]);
;                         *(u32x4*)(ob + row * 2048 + col) = w;
	v_lshlrev_b32_e32 v77, 16, v201
	v_lshlrev_b32_e32 v76, 16, v200
	v_and_b32_e32 v69, 0xffff0000, v201
	v_and_b32_e32 v68, 0xffff0000, v200
	v_lshlrev_b32_e32 v61, 16, v215
	v_lshlrev_b32_e32 v60, 16, v214
	v_and_b32_e32 v73, 0xffff0000, v215
	v_and_b32_e32 v72, 0xffff0000, v214
	v_pk_fma_f32 v[62:63], v[62:63], v[68:69], v[72:73]
	v_lshlrev_b32_e32 v69, 16, v203
	v_lshlrev_b32_e32 v68, 16, v202
	v_mov_b32_e32 v72, v56
	v_mov_b32_e32 v73, v58
	v_mov_b32_e32 v58, v57
	v_lshlrev_b32_e32 v57, 16, v217
	v_lshlrev_b32_e32 v56, 16, v216
	v_and_b32_e32 v71, 0xffff0000, v203
	v_and_b32_e32 v70, 0xffff0000, v202
	v_pk_fma_f32 v[56:57], v[72:73], v[68:69], v[56:57]
	v_and_b32_e32 v69, 0xffff0000, v217
	v_and_b32_e32 v68, 0xffff0000, v216
	v_pk_fma_f32 v[58:59], v[58:59], v[70:71], v[68:69]
	v_pk_fma_f32 v[60:61], v[78:79], v[76:77], v[60:61]
	v_cvt_pk_bf16_f32 v59, v57, v59
	v_cvt_pk_bf16_f32 v58, v56, v58
	v_cvt_pk_bf16_f32 v57, v61, v63
	v_cvt_pk_bf16_f32 v56, v60, v62
	global_store_dwordx4 v[64:65], v[56:59], off
	v_mov_b32_e32 v68, v52
	v_mov_b32_e32 v69, v54
	v_lshl_add_u64 v[56:57], v[66:67], 0, v[124:125]
	s_nop 0
	v_mov_b32_e32 v54, v53
	v_lshlrev_b32_e32 v67, 16, v219
	v_lshlrev_b32_e32 v66, 16, v218
	v_and_b32_e32 v57, 0xffff0000, v219
	v_and_b32_e32 v56, 0xffff0000, v218
	v_lshlrev_b32_e32 v53, 16, v223
	v_lshlrev_b32_e32 v52, 16, v222
	v_and_b32_e32 v61, 0xffff0000, v223
	v_and_b32_e32 v60, 0xffff0000, v222
	v_pk_fma_f32 v[54:55], v[54:55], v[56:57], v[60:61]
	v_lshlrev_b32_e32 v57, 16, v221
	v_lshlrev_b32_e32 v56, 16, v220
	v_mov_b32_e32 v60, v48
	v_mov_b32_e32 v61, v50
	v_mov_b32_e32 v50, v49
	v_lshlrev_b32_e32 v49, 16, v225
	v_lshlrev_b32_e32 v48, 16, v224
	v_and_b32_e32 v59, 0xffff0000, v221
	v_and_b32_e32 v58, 0xffff0000, v220
	v_pk_fma_f32 v[48:49], v[60:61], v[56:57], v[48:49]
	v_and_b32_e32 v57, 0xffff0000, v225
	v_and_b32_e32 v56, 0xffff0000, v224
	v_pk_fma_f32 v[50:51], v[50:51], v[58:59], v[56:57]
	v_pk_fma_f32 v[52:53], v[68:69], v[66:67], v[52:53]
	v_cvt_pk_bf16_f32 v51, v49, v51
	v_cvt_pk_bf16_f32 v50, v48, v50
	v_cvt_pk_bf16_f32 v49, v53, v55
	v_cvt_pk_bf16_f32 v48, v52, v54
	global_store_dwordx4 v[64:65], v[48:51], off offset:256
	v_mov_b32_e32 v62, v44
	v_mov_b32_e32 v63, v46
	v_add_u32_e32 v48, 0x90, v140
	v_ashrrev_i32_e32 v49, 31, v48
	v_lshlrev_b64 v[50:51], 13, v[48:49]
	v_lshlrev_b64 v[48:49], 12, v[48:49]
	v_lshl_add_u64 v[50:51], s[24:25], 0, v[50:51]
	v_lshl_add_u64 v[50:51], v[50:51], 0, s[8:9]
	v_lshl_add_u64 v[48:49], s[26:27], 0, v[48:49]
	v_lshl_add_u64 v[52:53], v[50:51], 0, v[138:139]
	v_lshl_add_u64 v[48:49], v[48:49], 0, v[138:139]
	v_add_u32_e32 v186, 0xa0, v140
	v_ashrrev_i32_e32 v187, 31, v186
	v_lshlrev_b64 v[188:189], 13, v[186:187]
	v_lshl_add_u64 v[188:189], s[24:25], 0, v[188:189]
	v_lshl_add_u64 v[188:189], v[188:189], 0, s[8:9]
	v_lshl_add_u64 v[190:191], v[188:189], 0, v[138:139]
	global_load_dwordx4 v[200:203], v[190:191], off
	v_add_u32_e32 v186, 0xa0, v140
	v_ashrrev_i32_e32 v187, 31, v186
	v_lshlrev_b64 v[186:187], 12, v[186:187]
	v_lshl_add_u64 v[186:187], s[26:27], 0, v[186:187]
	v_lshl_add_u64 v[186:187], v[186:187], 0, v[138:139]
	global_load_dwordx4 v[214:217], v[186:187], off
	v_or_b32_e32 v186, 0x80, v156
	v_ashrrev_i32_e32 v187, 31, v186
	v_lshlrev_b64 v[188:189], 1, v[186:187]
	v_add_u32_e32 v190, 0xa0, v140
	v_ashrrev_i32_e32 v191, 31, v190
	v_lshlrev_b64 v[192:193], 13, v[190:191]
	v_lshl_add_u64 v[192:193], s[24:25], 0, v[192:193]
	v_lshl_add_u64 v[192:193], v[192:193], 0, s[8:9]
	v_lshl_add_u64 v[194:195], v[192:193], 0, v[188:189]
	global_load_dwordx4 v[218:221], v[194:195], off
	v_add_u32_e32 v186, 0xa0, v140
	v_ashrrev_i32_e32 v187, 31, v186
	v_lshlrev_b64 v[186:187], 12, v[186:187]
	v_lshl_add_u64 v[186:187], s[26:27], 0, v[186:187]
	v_lshl_add_u64 v[186:187], v[186:187], 0, v[138:139]
	global_load_dwordx4 v[222:225], v[186:187], off offset:256
	v_mov_b32_e32 v46, v45
	s_waitcnt vmcnt(6)
	v_lshlrev_b32_e32 v61, 16, v227
	v_lshlrev_b32_e32 v60, 16, v226
	v_and_b32_e32 v53, 0xffff0000, v227
	v_and_b32_e32 v52, 0xffff0000, v226
	v_lshlrev_b32_e32 v45, 16, v231
	v_lshlrev_b32_e32 v44, 16, v230
	v_and_b32_e32 v57, 0xffff0000, v231
	v_and_b32_e32 v56, 0xffff0000, v230
	v_pk_fma_f32 v[46:47], v[46:47], v[52:53], v[56:57]
	v_lshlrev_b32_e32 v53, 16, v229
	v_lshlrev_b32_e32 v52, 16, v228
	v_mov_b32_e32 v56, v40
	v_mov_b32_e32 v57, v42
	v_mov_b32_e32 v42, v41
	v_lshlrev_b32_e32 v41, 16, v233
	v_lshlrev_b32_e32 v40, 16, v232
	v_and_b32_e32 v55, 0xffff0000, v229
	v_and_b32_e32 v54, 0xffff0000, v228
	v_pk_fma_f32 v[40:41], v[56:57], v[52:53], v[40:41]
	v_and_b32_e32 v53, 0xffff0000, v233
	v_and_b32_e32 v52, 0xffff0000, v232
	v_pk_fma_f32 v[42:43], v[42:43], v[54:55], v[52:53]
	v_pk_fma_f32 v[44:45], v[62:63], v[60:61], v[44:45]
	v_cvt_pk_bf16_f32 v43, v41, v43
	v_cvt_pk_bf16_f32 v42, v40, v42
	v_cvt_pk_bf16_f32 v41, v45, v47
	v_cvt_pk_bf16_f32 v40, v44, v46
	global_store_dwordx4 v[48:49], v[40:43], off
	v_mov_b32_e32 v52, v36
	v_mov_b32_e32 v53, v38
	v_lshl_add_u64 v[40:41], v[50:51], 0, v[124:125]
	s_nop 0
	v_mov_b32_e32 v38, v37
	v_lshlrev_b32_e32 v51, 16, v235
	v_lshlrev_b32_e32 v50, 16, v234
	v_and_b32_e32 v41, 0xffff0000, v235
	v_and_b32_e32 v40, 0xffff0000, v234
	v_lshlrev_b32_e32 v37, 16, v239
	v_lshlrev_b32_e32 v36, 16, v238
	v_and_b32_e32 v45, 0xffff0000, v239
	v_and_b32_e32 v44, 0xffff0000, v238
	v_pk_fma_f32 v[38:39], v[38:39], v[40:41], v[44:45]
	v_lshlrev_b32_e32 v41, 16, v237
	v_lshlrev_b32_e32 v40, 16, v236
	v_mov_b32_e32 v44, v32
	v_mov_b32_e32 v45, v34
	v_mov_b32_e32 v34, v33
	v_lshlrev_b32_e32 v33, 16, v241
	v_lshlrev_b32_e32 v32, 16, v240
	v_and_b32_e32 v43, 0xffff0000, v237
; __device__ __forceinline__ unsigned pk2(float lo, float hi) { return f2bf(lo) | (f2bf(hi) << 16); }
;     __device__ __forceinline__ void operator()(const f32x4 (&acc)[2][2][4][2], const pg8::Unit& u, int wr, int wc, int fr, int fq) const {
;     ...
;                     } else if constexpr (MODE == 2 || MODE == 3) {
;                         const u32x4 g = *(const u32x4*)(aux + row * 4096 + (MODE == 3 ? 2048 : 0) + col);
;                         float r[8] = {v0[0], v0[1], v0[2], v0[3], v1[0], v1[1], v1[2], v1[3]};
;                         const unsigned gw[4] = {g.x, g.y, g.z, g.w};
; #pragma unroll
;                         for (int i = 0; i < 4; ++i) { r[2 * i] *= bf2f(gw[i] & 0xffffu); r[2 * i + 1] *= __builtin_bit_cast(float, gw[i] & 0xffff0000u); }
;                         if constexpr (MODE == 3) { const u32x4 pv = *(const u32x4*)(ob + row * 2048 + col); const unsigned pw[4] = {pv.x, pv.y, pv.z, pv.w};
; #pragma unroll
;                             for (int i = 0; i < 4; ++i) { r[2 * i] += bf2f(pw[i] & 0xffffu); r[2 * i + 1] += __builtin_bit_cast(float, pw[i] & 0xffff0000u); } }
;                         u32x4 w; w.x = pk2(r[0], r[1]); w.y = pk2(r[2], r[3]); w.z = pk2(r[4], r[5]); w.w = pk2(r[6], r[7]);
;                         *(u32x4*)(ob + row * 2048 + col) = w;
	v_and_b32_e32 v42, 0xffff0000, v236
	v_pk_fma_f32 v[32:33], v[44:45], v[40:41], v[32:33]
	v_and_b32_e32 v41, 0xffff0000, v241
	v_and_b32_e32 v40, 0xffff0000, v240
	v_pk_fma_f32 v[34:35], v[34:35], v[42:43], v[40:41]
	v_pk_fma_f32 v[36:37], v[52:53], v[50:51], v[36:37]
	v_cvt_pk_bf16_f32 v35, v33, v35
	v_cvt_pk_bf16_f32 v34, v32, v34
	v_cvt_pk_bf16_f32 v33, v37, v39
	v_cvt_pk_bf16_f32 v32, v36, v38
	global_store_dwordx4 v[48:49], v[32:35], off offset:256
	v_mov_b32_e32 v46, v28
	v_mov_b32_e32 v47, v30
	v_add_u32_e32 v32, 0xa0, v140
	v_ashrrev_i32_e32 v33, 31, v32
	v_lshlrev_b64 v[34:35], 13, v[32:33]
	v_lshlrev_b64 v[32:33], 12, v[32:33]
	v_lshl_add_u64 v[34:35], s[24:25], 0, v[34:35]
	v_lshl_add_u64 v[34:35], v[34:35], 0, s[8:9]
	v_lshl_add_u64 v[32:33], s[26:27], 0, v[32:33]
	v_lshl_add_u64 v[36:37], v[34:35], 0, v[138:139]
	v_lshl_add_u64 v[32:33], v[32:33], 0, v[138:139]
	v_add_u32_e32 v186, 0xb0, v140
	v_ashrrev_i32_e32 v187, 31, v186
	v_lshlrev_b64 v[188:189], 13, v[186:187]
	v_lshl_add_u64 v[188:189], s[24:25], 0, v[188:189]
	v_lshl_add_u64 v[188:189], v[188:189], 0, s[8:9]
	v_lshl_add_u64 v[190:191], v[188:189], 0, v[138:139]
	global_load_dwordx4 v[226:229], v[190:191], off
	v_add_u32_e32 v186, 0xb0, v140
	v_ashrrev_i32_e32 v187, 31, v186
	v_lshlrev_b64 v[186:187], 12, v[186:187]
	v_lshl_add_u64 v[186:187], s[26:27], 0, v[186:187]
	v_lshl_add_u64 v[186:187], v[186:187], 0, v[138:139]
	global_load_dwordx4 v[230:233], v[186:187], off
	v_or_b32_e32 v186, 0x80, v156
	v_ashrrev_i32_e32 v187, 31, v186
	v_lshlrev_b64 v[188:189], 1, v[186:187]
	v_add_u32_e32 v190, 0xb0, v140
	v_ashrrev_i32_e32 v191, 31, v190
	v_lshlrev_b64 v[192:193], 13, v[190:191]
	v_lshl_add_u64 v[192:193], s[24:25], 0, v[192:193]
	v_lshl_add_u64 v[192:193], v[192:193], 0, s[8:9]
	v_lshl_add_u64 v[194:195], v[192:193], 0, v[188:189]
	global_load_dwordx4 v[234:237], v[194:195], off
	v_add_u32_e32 v186, 0xb0, v140
	v_ashrrev_i32_e32 v187, 31, v186
	v_lshlrev_b64 v[186:187], 12, v[186:187]
	v_lshl_add_u64 v[186:187], s[26:27], 0, v[186:187]
	v_lshl_add_u64 v[186:187], v[186:187], 0, v[138:139]
	global_load_dwordx4 v[238:241], v[186:187], off offset:256
	v_mov_b32_e32 v30, v29
	s_waitcnt vmcnt(6)
	v_lshlrev_b32_e32 v45, 16, v201
	v_lshlrev_b32_e32 v44, 16, v200
	v_and_b32_e32 v37, 0xffff0000, v201
	v_and_b32_e32 v36, 0xffff0000, v200
	v_lshlrev_b32_e32 v29, 16, v215
	v_lshlrev_b32_e32 v28, 16, v214
	v_and_b32_e32 v41, 0xffff0000, v215
	v_and_b32_e32 v40, 0xffff0000, v214
	v_pk_fma_f32 v[30:31], v[30:31], v[36:37], v[40:41]
	v_lshlrev_b32_e32 v37, 16, v203
	v_lshlrev_b32_e32 v36, 16, v202
	v_mov_b32_e32 v40, v24
	v_mov_b32_e32 v41, v26
	v_mov_b32_e32 v26, v25
	v_lshlrev_b32_e32 v25, 16, v217
	v_lshlrev_b32_e32 v24, 16, v216
	v_and_b32_e32 v39, 0xffff0000, v203
	v_and_b32_e32 v38, 0xffff0000, v202
	v_pk_fma_f32 v[24:25], v[40:41], v[36:37], v[24:25]
	v_and_b32_e32 v37, 0xffff0000, v217
	v_and_b32_e32 v36, 0xffff0000, v216
	v_pk_fma_f32 v[26:27], v[26:27], v[38:39], v[36:37]
	v_pk_fma_f32 v[28:29], v[46:47], v[44:45], v[28:29]
	v_cvt_pk_bf16_f32 v27, v25, v27
	v_cvt_pk_bf16_f32 v26, v24, v26
	v_cvt_pk_bf16_f32 v25, v29, v31
	v_cvt_pk_bf16_f32 v24, v28, v30
	global_store_dwordx4 v[32:33], v[24:27], off
	v_mov_b32_e32 v36, v20
	v_mov_b32_e32 v37, v22
	v_lshl_add_u64 v[24:25], v[34:35], 0, v[124:125]
	s_nop 0
	v_mov_b32_e32 v22, v21
	v_lshlrev_b32_e32 v35, 16, v219
	v_lshlrev_b32_e32 v34, 16, v218
	v_and_b32_e32 v25, 0xffff0000, v219
	v_and_b32_e32 v24, 0xffff0000, v218
	v_lshlrev_b32_e32 v21, 16, v223
	v_lshlrev_b32_e32 v20, 16, v222
	v_and_b32_e32 v29, 0xffff0000, v223
	v_and_b32_e32 v28, 0xffff0000, v222
	v_pk_fma_f32 v[22:23], v[22:23], v[24:25], v[28:29]
	v_lshlrev_b32_e32 v25, 16, v221
	v_lshlrev_b32_e32 v24, 16, v220
	v_mov_b32_e32 v28, v16
	v_mov_b32_e32 v29, v18
	v_mov_b32_e32 v18, v17
	v_lshlrev_b32_e32 v17, 16, v225
	v_lshlrev_b32_e32 v16, 16, v224
	v_and_b32_e32 v27, 0xffff0000, v221
	v_and_b32_e32 v26, 0xffff0000, v220
	v_pk_fma_f32 v[16:17], v[28:29], v[24:25], v[16:17]
	v_and_b32_e32 v25, 0xffff0000, v225
	v_and_b32_e32 v24, 0xffff0000, v224
	v_pk_fma_f32 v[18:19], v[18:19], v[26:27], v[24:25]
	v_pk_fma_f32 v[20:21], v[36:37], v[34:35], v[20:21]
	v_cvt_pk_bf16_f32 v19, v17, v19
	v_cvt_pk_bf16_f32 v18, v16, v18
	v_cvt_pk_bf16_f32 v17, v21, v23
	v_cvt_pk_bf16_f32 v16, v20, v22
	global_store_dwordx4 v[32:33], v[16:19], off offset:256
	v_mov_b32_e32 v30, v12
	v_mov_b32_e32 v31, v14
	v_add_u32_e32 v16, 0xb0, v140
	v_ashrrev_i32_e32 v17, 31, v16
	v_lshlrev_b64 v[18:19], 13, v[16:17]
	v_lshlrev_b64 v[16:17], 12, v[16:17]
	v_lshl_add_u64 v[18:19], s[24:25], 0, v[18:19]
	v_lshl_add_u64 v[18:19], v[18:19], 0, s[8:9]
	v_lshl_add_u64 v[16:17], s[26:27], 0, v[16:17]
	v_lshl_add_u64 v[20:21], v[18:19], 0, v[138:139]
	v_lshl_add_u64 v[16:17], v[16:17], 0, v[138:139]
	v_mov_b32_e32 v14, v13
	s_waitcnt vmcnt(2)
	v_lshlrev_b32_e32 v29, 16, v227
	v_lshlrev_b32_e32 v28, 16, v226
	v_and_b32_e32 v21, 0xffff0000, v227
	v_and_b32_e32 v20, 0xffff0000, v226
	v_lshlrev_b32_e32 v13, 16, v231
	v_lshlrev_b32_e32 v12, 16, v230
	v_and_b32_e32 v25, 0xffff0000, v231
	v_and_b32_e32 v24, 0xffff0000, v230
	v_pk_fma_f32 v[14:15], v[14:15], v[20:21], v[24:25]
	v_lshlrev_b32_e32 v21, 16, v229
	v_lshlrev_b32_e32 v20, 16, v228
	v_mov_b32_e32 v24, v8
	v_mov_b32_e32 v25, v10
	v_mov_b32_e32 v10, v9
	v_lshlrev_b32_e32 v9, 16, v233
	v_lshlrev_b32_e32 v8, 16, v232
	v_and_b32_e32 v23, 0xffff0000, v229
	v_and_b32_e32 v22, 0xffff0000, v228
	v_pk_fma_f32 v[8:9], v[24:25], v[20:21], v[8:9]
	v_and_b32_e32 v21, 0xffff0000, v233
	v_and_b32_e32 v20, 0xffff0000, v232
	v_pk_fma_f32 v[10:11], v[10:11], v[22:23], v[20:21]
	v_pk_fma_f32 v[12:13], v[30:31], v[28:29], v[12:13]
	v_cvt_pk_bf16_f32 v11, v9, v11
	v_cvt_pk_bf16_f32 v10, v8, v10
	v_cvt_pk_bf16_f32 v9, v13, v15
	v_cvt_pk_bf16_f32 v8, v12, v14
	global_store_dwordx4 v[16:17], v[8:11], off
	v_mov_b32_e32 v20, v4
	v_mov_b32_e32 v21, v6
	v_lshl_add_u64 v[8:9], v[18:19], 0, v[124:125]
	s_nop 0
	v_mov_b32_e32 v6, v5
	v_lshlrev_b32_e32 v19, 16, v235
	v_lshlrev_b32_e32 v18, 16, v234
	v_and_b32_e32 v13, 0xffff0000, v235
	v_and_b32_e32 v12, 0xffff0000, v234
	v_lshlrev_b32_e32 v5, 16, v239
	v_lshlrev_b32_e32 v4, 16, v238
	v_and_b32_e32 v9, 0xffff0000, v239
	v_and_b32_e32 v8, 0xffff0000, v238
	v_pk_fma_f32 v[6:7], v[6:7], v[12:13], v[8:9]
	v_lshlrev_b32_e32 v9, 16, v237
	v_lshlrev_b32_e32 v8, 16, v236
	v_mov_b32_e32 v12, v0
	v_mov_b32_e32 v13, v2
	v_mov_b32_e32 v2, v1
	v_lshlrev_b32_e32 v1, 16, v241
	v_lshlrev_b32_e32 v0, 16, v240
	v_and_b32_e32 v15, 0xffff0000, v237
	v_and_b32_e32 v14, 0xffff0000, v236
	v_pk_fma_f32 v[0:1], v[12:13], v[8:9], v[0:1]
	v_and_b32_e32 v9, 0xffff0000, v241
	v_and_b32_e32 v8, 0xffff0000, v240
	v_pk_fma_f32 v[2:3], v[2:3], v[14:15], v[8:9]
	v_pk_fma_f32 v[4:5], v[20:21], v[18:19], v[4:5]
	v_cvt_pk_bf16_f32 v3, v1, v3
	v_cvt_pk_bf16_f32 v2, v0, v2
	v_cvt_pk_bf16_f32 v1, v5, v7
	v_cvt_pk_bf16_f32 v0, v4, v6
	global_store_dwordx4 v[16:17], v[0:3], off offset:256
	s_cbranch_vccnz .LBB0_109
; #define PG8_BAR __builtin_amdgcn_s_barrier()
; template <class Epi, class Sched, bool ALIGN_EPI = false, bool SP2 = false, bool F8 = false>
; __device__ __forceinline__ void gemm_phase(PG8_LAS unsigned char* lds, const Gemm g, const Sched& S, const Epi& E) {
;     ...
;         if constexpr (ALIGN_EPI) { if (wr == 0) PG8_BAR; }
;         if constexpr (F8) asm volatile("s_nop 15\n\ts_nop 15" : "+v"(acc[1][1][0][0]), "+v"(acc[1][1][0][1]), "+v"(acc[1][1][1][0]), "+v"(acc[1][1][1][1]), "+v"(acc[1][1][2][0]), "+v"(acc[1][1][2][1]), "+v"(acc[1][1][3][0]), "+v"(acc[1][1][3][1]));
;         if constexpr (!Epi::AFTER_DRAIN) { E(acc, cur, wr, wc, fr, fq); S.done(cur); }
;         if (!has_next) break;
; #pragma unroll
;         for (int a = 0; a < 2; ++a)
; #pragma unroll
;             for (int b = 0; b < 2; ++b)
; #pragma unroll
;                 for (int m = 0; m < 4; ++m)
; #pragma unroll
;                     for (int n = 0; n < 2; ++n) acc[a][b][m][n] = (f32x4){0.f, 0.f, 0.f, 0.f};
;         cur = nxt; cA = nA; cB = nB; ++ui;
;         if constexpr (ALIGN_EPI) { if (wr == 1) PG8_BAR; }
;     }
	s_andn2_b64 vcc, exec, s[0:1]
	s_cbranch_vccnz .LBB0_108
	s_barrier
	s_branch .LBB0_108
